# v7 + attention unit epilogue: O transposed through wave-local LDS and stored as 16-byte row segments instead of 128 two-byte stores per lane
# speedup vs baseline: 1.0063x; 1.0063x over previous
; __device__ __forceinline__ unsigned cvtpk(float lo, float hi) { unsigned r; asm volatile("v_cvt_pk_bf16_f32 %0, %1, %2" : "=v"(r) : "v"(lo), "v"(hi)); return r; }
; __device__ __forceinline__ int crow(int r, int hi) { return (r & 3) + 8 * (r >> 2) + 4 * hi; }
; __device__ __forceinline__ void body(const bf16_t* __restrict__ Qb, const bf16_t* __restrict__ Kh, const bf16_t* __restrict__ Vh, bf16_t* __restrict__ Ob, int seq, char* lds) {
;     ...
;   if (hi == 0) li_l[r32] = l_reg; asm volatile("s_waitcnt lgkmcnt(0)" ::: "memory");
;   float rli[16];
; #pragma unroll
;   for (int r = 0; r < 16; ++r) rli[r] = __builtin_amdgcn_rcpf(li_l[crow(r, hi)]);
;   bf16_t* Ow = Ob + (long)(wid * QBLK) * LDO;
; #pragma unroll
;   for (int r = 0; r < 16; ++r) { int orow = crow(r, hi);
; #pragma unroll
;     for (int d0 = 0; d0 < 8; ++d0) Ow[(long)orow * LDO + d0 * 32 + r32] = (bf16_t)(cvtpk(o[d0][r] * rli[r], 0.f) & 0xffff); }
.LBB0_607:
	s_or_b64 exec, exec, s[8:9]
	s_waitcnt lgkmcnt(0)
	v_add_u32_e32 v1, v211, v212
	ds_read_b128 v[130:133], v1
	ds_read_b128 v[134:137], v1 offset:32
	ds_read_b128 v[138:141], v1 offset:64
	ds_read_b128 v[142:145], v1 offset:96
	s_mul_hi_i32 s7, s25, 0x1100
	s_mulk_i32 s25, 0x1100
	s_lshl_b32 s6, s21, 8
	s_add_u32 s6, s25, s6
	s_addc_u32 s7, s7, 0
	s_lshl_b64 s[6:7], s[6:7], 12
	s_add_u32 s6, s17, s6
	s_addc_u32 s7, s18, s7
	s_lshl_b32 s8, s19, 9
	s_and_b32 s8, s8, 0xe00
	s_add_u32 s6, s6, s8
	s_addc_u32 s7, s7, 0
	s_mov_b32 s42, 0x4000
	s_mov_b32 s43, 0
	v_and_b32_e32 v148, 63, v220
	v_lshlrev_b32_e32 v146, 8, v210
	v_lshlrev_b32_e32 v147, 4, v148
	v_add3_u32 v147, v147, v146, 16
	v_lshl_add_u32 v146, v232, 10, v146
	v_lshl_add_u32 v146, v231, 1, v146
	v_add_u32_e32 v146, 16, v146
	v_lshrrev_b32_e32 v149, 4, v148
	v_add_u32_e32 v149, v149, v210
	v_lshlrev_b32_e32 v149, 12, v149
	v_and_b32_e32 v148, 15, v148
	v_lshl_add_u32 v150, v148, 4, v149
	v_mov_b32_e32 v151, v0
	v_lshl_add_u64 v[150:151], s[6:7], 0, v[150:151]
	s_waitcnt lgkmcnt(0)
	v_rcp_f32_e32 v130, v130
	v_rcp_f32_e32 v131, v131
	v_rcp_f32_e32 v132, v132
	v_rcp_f32_e32 v133, v133
	v_rcp_f32_e32 v134, v134
	v_rcp_f32_e32 v135, v135
	v_rcp_f32_e32 v136, v136
	v_rcp_f32_e32 v137, v137
	v_rcp_f32_e32 v138, v138
	v_rcp_f32_e32 v139, v139
	v_rcp_f32_e32 v140, v140
	v_rcp_f32_e32 v141, v141
	v_rcp_f32_e32 v142, v142
	v_rcp_f32_e32 v143, v143
	v_rcp_f32_e32 v144, v144
	v_rcp_f32_e32 v145, v145
	v_mul_f32_e32 v114, v114, v130
	v_cvt_pk_bf16_f32 v114, v114, v0
	ds_write_b16 v146, v114 offset:0
	v_mul_f32_e32 v115, v115, v131
	v_cvt_pk_bf16_f32 v115, v115, v0
	ds_write_b16 v146, v115 offset:256
	v_mul_f32_e32 v116, v116, v132
	v_cvt_pk_bf16_f32 v116, v116, v0
	ds_write_b16 v146, v116 offset:512
	v_mul_f32_e32 v117, v117, v133
	v_cvt_pk_bf16_f32 v117, v117, v0
	ds_write_b16 v146, v117 offset:768
	v_mul_f32_e32 v118, v118, v134
	v_cvt_pk_bf16_f32 v118, v118, v0
	ds_write_b16 v146, v118 offset:2048
	v_mul_f32_e32 v119, v119, v135
	v_cvt_pk_bf16_f32 v119, v119, v0
	ds_write_b16 v146, v119 offset:2304
	v_mul_f32_e32 v120, v120, v136
	v_cvt_pk_bf16_f32 v120, v120, v0
	ds_write_b16 v146, v120 offset:2560
	v_mul_f32_e32 v121, v121, v137
	v_cvt_pk_bf16_f32 v121, v121, v0
	ds_write_b16 v146, v121 offset:2816
	v_mul_f32_e32 v122, v122, v138
	v_cvt_pk_bf16_f32 v122, v122, v0
	ds_write_b16 v146, v122 offset:4096
	v_mul_f32_e32 v123, v123, v139
	v_cvt_pk_bf16_f32 v123, v123, v0
	ds_write_b16 v146, v123 offset:4352
	v_mul_f32_e32 v124, v124, v140
	v_cvt_pk_bf16_f32 v124, v124, v0
	ds_write_b16 v146, v124 offset:4608
	v_mul_f32_e32 v125, v125, v141
	v_cvt_pk_bf16_f32 v125, v125, v0
	ds_write_b16 v146, v125 offset:4864
	v_mul_f32_e32 v126, v126, v142
	v_cvt_pk_bf16_f32 v126, v126, v0
	ds_write_b16 v146, v126 offset:6144
	v_mul_f32_e32 v127, v127, v143
	v_cvt_pk_bf16_f32 v127, v127, v0
	ds_write_b16 v146, v127 offset:6400
	v_mul_f32_e32 v128, v128, v144
	v_cvt_pk_bf16_f32 v128, v128, v0
	ds_write_b16 v146, v128 offset:6656
	v_mul_f32_e32 v129, v129, v145
	v_cvt_pk_bf16_f32 v129, v129, v0
	ds_write_b16 v146, v129 offset:6912
	v_mul_f32_e32 v98, v98, v130
	v_cvt_pk_bf16_f32 v98, v98, v0
	ds_write_b16 v146, v98 offset:64
	v_mul_f32_e32 v99, v99, v131
	v_cvt_pk_bf16_f32 v99, v99, v0
	ds_write_b16 v146, v99 offset:320
	v_mul_f32_e32 v100, v100, v132
	v_cvt_pk_bf16_f32 v100, v100, v0
	ds_write_b16 v146, v100 offset:576
	v_mul_f32_e32 v101, v101, v133
	v_cvt_pk_bf16_f32 v101, v101, v0
	ds_write_b16 v146, v101 offset:832
	v_mul_f32_e32 v102, v102, v134
	v_cvt_pk_bf16_f32 v102, v102, v0
	ds_write_b16 v146, v102 offset:2112
	v_mul_f32_e32 v103, v103, v135
	v_cvt_pk_bf16_f32 v103, v103, v0
	ds_write_b16 v146, v103 offset:2368
	v_mul_f32_e32 v104, v104, v136
	v_cvt_pk_bf16_f32 v104, v104, v0
	ds_write_b16 v146, v104 offset:2624
	v_mul_f32_e32 v105, v105, v137
	v_cvt_pk_bf16_f32 v105, v105, v0
	ds_write_b16 v146, v105 offset:2880
	v_mul_f32_e32 v106, v106, v138
	v_cvt_pk_bf16_f32 v106, v106, v0
	ds_write_b16 v146, v106 offset:4160
	v_mul_f32_e32 v107, v107, v139
	v_cvt_pk_bf16_f32 v107, v107, v0
	ds_write_b16 v146, v107 offset:4416
	v_mul_f32_e32 v108, v108, v140
	v_cvt_pk_bf16_f32 v108, v108, v0
	ds_write_b16 v146, v108 offset:4672
	v_mul_f32_e32 v109, v109, v141
	v_cvt_pk_bf16_f32 v109, v109, v0
	ds_write_b16 v146, v109 offset:4928
	v_mul_f32_e32 v110, v110, v142
	v_cvt_pk_bf16_f32 v110, v110, v0
	ds_write_b16 v146, v110 offset:6208
	v_mul_f32_e32 v111, v111, v143
	v_cvt_pk_bf16_f32 v111, v111, v0
	ds_write_b16 v146, v111 offset:6464
	v_mul_f32_e32 v112, v112, v144
	v_cvt_pk_bf16_f32 v112, v112, v0
	ds_write_b16 v146, v112 offset:6720
	v_mul_f32_e32 v113, v113, v145
	v_cvt_pk_bf16_f32 v113, v113, v0
	ds_write_b16 v146, v113 offset:6976
	v_mul_f32_e32 v82, v82, v130
	v_cvt_pk_bf16_f32 v82, v82, v0
	ds_write_b16 v146, v82 offset:128
	v_mul_f32_e32 v83, v83, v131
	v_cvt_pk_bf16_f32 v83, v83, v0
	ds_write_b16 v146, v83 offset:384
	v_mul_f32_e32 v84, v84, v132
	v_cvt_pk_bf16_f32 v84, v84, v0
	ds_write_b16 v146, v84 offset:640
	v_mul_f32_e32 v85, v85, v133
	v_cvt_pk_bf16_f32 v85, v85, v0
	ds_write_b16 v146, v85 offset:896
	v_mul_f32_e32 v86, v86, v134
	v_cvt_pk_bf16_f32 v86, v86, v0
	ds_write_b16 v146, v86 offset:2176
	v_mul_f32_e32 v87, v87, v135
	v_cvt_pk_bf16_f32 v87, v87, v0
	ds_write_b16 v146, v87 offset:2432
	v_mul_f32_e32 v88, v88, v136
	v_cvt_pk_bf16_f32 v88, v88, v0
	ds_write_b16 v146, v88 offset:2688
	v_mul_f32_e32 v89, v89, v137
	v_cvt_pk_bf16_f32 v89, v89, v0
	ds_write_b16 v146, v89 offset:2944
	v_mul_f32_e32 v90, v90, v138
	v_cvt_pk_bf16_f32 v90, v90, v0
	ds_write_b16 v146, v90 offset:4224
; __device__ __forceinline__ unsigned cvtpk(float lo, float hi) { unsigned r; asm volatile("v_cvt_pk_bf16_f32 %0, %1, %2" : "=v"(r) : "v"(lo), "v"(hi)); return r; }
; __device__ __forceinline__ int crow(int r, int hi) { return (r & 3) + 8 * (r >> 2) + 4 * hi; }
; __device__ __forceinline__ void body(const bf16_t* __restrict__ Qb, const bf16_t* __restrict__ Kh, const bf16_t* __restrict__ Vh, bf16_t* __restrict__ Ob, int seq, char* lds) {
;     ...
;   bf16_t* Ow = Ob + (long)(wid * QBLK) * LDO;
; #pragma unroll
;   for (int r = 0; r < 16; ++r) { int orow = crow(r, hi);
; #pragma unroll
;     for (int d0 = 0; d0 < 8; ++d0) Ow[(long)orow * LDO + d0 * 32 + r32] = (bf16_t)(cvtpk(o[d0][r] * rli[r], 0.f) & 0xffff); }
	v_mul_f32_e32 v91, v91, v139
	v_cvt_pk_bf16_f32 v91, v91, v0
	ds_write_b16 v146, v91 offset:4480
	v_mul_f32_e32 v92, v92, v140
	v_cvt_pk_bf16_f32 v92, v92, v0
	ds_write_b16 v146, v92 offset:4736
	v_mul_f32_e32 v93, v93, v141
	v_cvt_pk_bf16_f32 v93, v93, v0
	ds_write_b16 v146, v93 offset:4992
	v_mul_f32_e32 v94, v94, v142
	v_cvt_pk_bf16_f32 v94, v94, v0
	ds_write_b16 v146, v94 offset:6272
	v_mul_f32_e32 v95, v95, v143
	v_cvt_pk_bf16_f32 v95, v95, v0
	ds_write_b16 v146, v95 offset:6528
	v_mul_f32_e32 v96, v96, v144
	v_cvt_pk_bf16_f32 v96, v96, v0
	ds_write_b16 v146, v96 offset:6784
	v_mul_f32_e32 v97, v97, v145
	v_cvt_pk_bf16_f32 v97, v97, v0
	ds_write_b16 v146, v97 offset:7040
	v_mul_f32_e32 v66, v66, v130
	v_cvt_pk_bf16_f32 v66, v66, v0
	ds_write_b16 v146, v66 offset:192
	v_mul_f32_e32 v67, v67, v131
	v_cvt_pk_bf16_f32 v67, v67, v0
	ds_write_b16 v146, v67 offset:448
	v_mul_f32_e32 v68, v68, v132
	v_cvt_pk_bf16_f32 v68, v68, v0
	ds_write_b16 v146, v68 offset:704
	v_mul_f32_e32 v69, v69, v133
	v_cvt_pk_bf16_f32 v69, v69, v0
	ds_write_b16 v146, v69 offset:960
	v_mul_f32_e32 v70, v70, v134
	v_cvt_pk_bf16_f32 v70, v70, v0
	ds_write_b16 v146, v70 offset:2240
	v_mul_f32_e32 v71, v71, v135
	v_cvt_pk_bf16_f32 v71, v71, v0
	ds_write_b16 v146, v71 offset:2496
	v_mul_f32_e32 v72, v72, v136
	v_cvt_pk_bf16_f32 v72, v72, v0
	ds_write_b16 v146, v72 offset:2752
	v_mul_f32_e32 v73, v73, v137
	v_cvt_pk_bf16_f32 v73, v73, v0
	ds_write_b16 v146, v73 offset:3008
	v_mul_f32_e32 v74, v74, v138
	v_cvt_pk_bf16_f32 v74, v74, v0
	ds_write_b16 v146, v74 offset:4288
	v_mul_f32_e32 v75, v75, v139
	v_cvt_pk_bf16_f32 v75, v75, v0
	ds_write_b16 v146, v75 offset:4544
	v_mul_f32_e32 v76, v76, v140
	v_cvt_pk_bf16_f32 v76, v76, v0
	ds_write_b16 v146, v76 offset:4800
	v_mul_f32_e32 v77, v77, v141
	v_cvt_pk_bf16_f32 v77, v77, v0
	ds_write_b16 v146, v77 offset:5056
	v_mul_f32_e32 v78, v78, v142
	v_cvt_pk_bf16_f32 v78, v78, v0
	ds_write_b16 v146, v78 offset:6336
	v_mul_f32_e32 v79, v79, v143
	v_cvt_pk_bf16_f32 v79, v79, v0
	ds_write_b16 v146, v79 offset:6592
	v_mul_f32_e32 v80, v80, v144
	v_cvt_pk_bf16_f32 v80, v80, v0
	ds_write_b16 v146, v80 offset:6848
	v_mul_f32_e32 v81, v81, v145
	v_cvt_pk_bf16_f32 v81, v81, v0
	ds_write_b16 v146, v81 offset:7104
	v_lshl_add_u64 v[98:99], v[150:151], 0, s[42:43]
	v_lshl_add_u64 v[100:101], v[98:99], 0, s[42:43]
	v_lshl_add_u64 v[102:103], v[100:101], 0, s[42:43]
	v_lshl_add_u64 v[104:105], v[102:103], 0, s[42:43]
	v_lshl_add_u64 v[106:107], v[104:105], 0, s[42:43]
	v_lshl_add_u64 v[108:109], v[106:107], 0, s[42:43]
	v_lshl_add_u64 v[110:111], v[108:109], 0, s[42:43]
	s_waitcnt lgkmcnt(0)
	ds_read_b128 v[66:69], v147 offset:0
	ds_read_b128 v[70:73], v147 offset:1024
	ds_read_b128 v[74:77], v147 offset:2048
	ds_read_b128 v[78:81], v147 offset:3072
	ds_read_b128 v[82:85], v147 offset:4096
	ds_read_b128 v[86:89], v147 offset:5120
	ds_read_b128 v[90:93], v147 offset:6144
	ds_read_b128 v[94:97], v147 offset:7168
	s_waitcnt lgkmcnt(7)
	global_store_dwordx4 v[150:151], v[66:69], off
	s_waitcnt lgkmcnt(6)
	global_store_dwordx4 v[98:99], v[70:73], off
	s_waitcnt lgkmcnt(5)
	global_store_dwordx4 v[100:101], v[74:77], off
	s_waitcnt lgkmcnt(4)
	global_store_dwordx4 v[102:103], v[78:81], off
	s_waitcnt lgkmcnt(3)
	global_store_dwordx4 v[104:105], v[82:85], off
	s_waitcnt lgkmcnt(2)
	global_store_dwordx4 v[106:107], v[86:89], off
	s_waitcnt lgkmcnt(1)
	global_store_dwordx4 v[108:109], v[90:93], off
	s_waitcnt lgkmcnt(0)
	global_store_dwordx4 v[110:111], v[94:97], off
	v_mul_f32_e32 v50, v50, v130
	v_cvt_pk_bf16_f32 v50, v50, v0
	ds_write_b16 v146, v50 offset:0
	v_mul_f32_e32 v51, v51, v131
	v_cvt_pk_bf16_f32 v51, v51, v0
	ds_write_b16 v146, v51 offset:256
	v_mul_f32_e32 v52, v52, v132
	v_cvt_pk_bf16_f32 v52, v52, v0
	ds_write_b16 v146, v52 offset:512
	v_mul_f32_e32 v53, v53, v133
	v_cvt_pk_bf16_f32 v53, v53, v0
	ds_write_b16 v146, v53 offset:768
	v_mul_f32_e32 v54, v54, v134
	v_cvt_pk_bf16_f32 v54, v54, v0
	ds_write_b16 v146, v54 offset:2048
	v_mul_f32_e32 v55, v55, v135
	v_cvt_pk_bf16_f32 v55, v55, v0
	ds_write_b16 v146, v55 offset:2304
	v_mul_f32_e32 v56, v56, v136
	v_cvt_pk_bf16_f32 v56, v56, v0
	ds_write_b16 v146, v56 offset:2560
	v_mul_f32_e32 v57, v57, v137
	v_cvt_pk_bf16_f32 v57, v57, v0
	ds_write_b16 v146, v57 offset:2816
	v_mul_f32_e32 v58, v58, v138
	v_cvt_pk_bf16_f32 v58, v58, v0
	ds_write_b16 v146, v58 offset:4096
	v_mul_f32_e32 v59, v59, v139
	v_cvt_pk_bf16_f32 v59, v59, v0
	ds_write_b16 v146, v59 offset:4352
	v_mul_f32_e32 v60, v60, v140
	v_cvt_pk_bf16_f32 v60, v60, v0
	ds_write_b16 v146, v60 offset:4608
	v_mul_f32_e32 v61, v61, v141
	v_cvt_pk_bf16_f32 v61, v61, v0
	ds_write_b16 v146, v61 offset:4864
	v_mul_f32_e32 v62, v62, v142
	v_cvt_pk_bf16_f32 v62, v62, v0
	ds_write_b16 v146, v62 offset:6144
	v_mul_f32_e32 v63, v63, v143
	v_cvt_pk_bf16_f32 v63, v63, v0
	ds_write_b16 v146, v63 offset:6400
	v_mul_f32_e32 v64, v64, v144
	v_cvt_pk_bf16_f32 v64, v64, v0
	ds_write_b16 v146, v64 offset:6656
	v_mul_f32_e32 v65, v65, v145
	v_cvt_pk_bf16_f32 v65, v65, v0
	ds_write_b16 v146, v65 offset:6912
	v_mul_f32_e32 v34, v34, v130
	v_cvt_pk_bf16_f32 v34, v34, v0
	ds_write_b16 v146, v34 offset:64
	v_mul_f32_e32 v35, v35, v131
	v_cvt_pk_bf16_f32 v35, v35, v0
	ds_write_b16 v146, v35 offset:320
	v_mul_f32_e32 v36, v36, v132
	v_cvt_pk_bf16_f32 v36, v36, v0
	ds_write_b16 v146, v36 offset:576
	v_mul_f32_e32 v37, v37, v133
	v_cvt_pk_bf16_f32 v37, v37, v0
	ds_write_b16 v146, v37 offset:832
; __device__ __forceinline__ unsigned cvtpk(float lo, float hi) { unsigned r; asm volatile("v_cvt_pk_bf16_f32 %0, %1, %2" : "=v"(r) : "v"(lo), "v"(hi)); return r; }
; __device__ __forceinline__ int crow(int r, int hi) { return (r & 3) + 8 * (r >> 2) + 4 * hi; }
; __device__ __forceinline__ void body(const bf16_t* __restrict__ Qb, const bf16_t* __restrict__ Kh, const bf16_t* __restrict__ Vh, bf16_t* __restrict__ Ob, int seq, char* lds) {
;     ...
;   bf16_t* Ow = Ob + (long)(wid * QBLK) * LDO;
; #pragma unroll
;   for (int r = 0; r < 16; ++r) { int orow = crow(r, hi);
; #pragma unroll
;     for (int d0 = 0; d0 < 8; ++d0) Ow[(long)orow * LDO + d0 * 32 + r32] = (bf16_t)(cvtpk(o[d0][r] * rli[r], 0.f) & 0xffff); }
;     ...
;   __syncthreads();
; }
	v_mul_f32_e32 v38, v38, v134
	v_cvt_pk_bf16_f32 v38, v38, v0
	ds_write_b16 v146, v38 offset:2112
	v_mul_f32_e32 v39, v39, v135
	v_cvt_pk_bf16_f32 v39, v39, v0
	ds_write_b16 v146, v39 offset:2368
	v_mul_f32_e32 v40, v40, v136
	v_cvt_pk_bf16_f32 v40, v40, v0
	ds_write_b16 v146, v40 offset:2624
	v_mul_f32_e32 v41, v41, v137
	v_cvt_pk_bf16_f32 v41, v41, v0
	ds_write_b16 v146, v41 offset:2880
	v_mul_f32_e32 v42, v42, v138
	v_cvt_pk_bf16_f32 v42, v42, v0
	ds_write_b16 v146, v42 offset:4160
	v_mul_f32_e32 v43, v43, v139
	v_cvt_pk_bf16_f32 v43, v43, v0
	ds_write_b16 v146, v43 offset:4416
	v_mul_f32_e32 v44, v44, v140
	v_cvt_pk_bf16_f32 v44, v44, v0
	ds_write_b16 v146, v44 offset:4672
	v_mul_f32_e32 v45, v45, v141
	v_cvt_pk_bf16_f32 v45, v45, v0
	ds_write_b16 v146, v45 offset:4928
	v_mul_f32_e32 v46, v46, v142
	v_cvt_pk_bf16_f32 v46, v46, v0
	ds_write_b16 v146, v46 offset:6208
	v_mul_f32_e32 v47, v47, v143
	v_cvt_pk_bf16_f32 v47, v47, v0
	ds_write_b16 v146, v47 offset:6464
	v_mul_f32_e32 v48, v48, v144
	v_cvt_pk_bf16_f32 v48, v48, v0
	ds_write_b16 v146, v48 offset:6720
	v_mul_f32_e32 v49, v49, v145
	v_cvt_pk_bf16_f32 v49, v49, v0
	ds_write_b16 v146, v49 offset:6976
	v_mul_f32_e32 v18, v18, v130
	v_cvt_pk_bf16_f32 v18, v18, v0
	ds_write_b16 v146, v18 offset:128
	v_mul_f32_e32 v19, v19, v131
	v_cvt_pk_bf16_f32 v19, v19, v0
	ds_write_b16 v146, v19 offset:384
	v_mul_f32_e32 v20, v20, v132
	v_cvt_pk_bf16_f32 v20, v20, v0
	ds_write_b16 v146, v20 offset:640
	v_mul_f32_e32 v21, v21, v133
	v_cvt_pk_bf16_f32 v21, v21, v0
	ds_write_b16 v146, v21 offset:896
	v_mul_f32_e32 v22, v22, v134
	v_cvt_pk_bf16_f32 v22, v22, v0
	ds_write_b16 v146, v22 offset:2176
	v_mul_f32_e32 v23, v23, v135
	v_cvt_pk_bf16_f32 v23, v23, v0
	ds_write_b16 v146, v23 offset:2432
	v_mul_f32_e32 v24, v24, v136
	v_cvt_pk_bf16_f32 v24, v24, v0
	ds_write_b16 v146, v24 offset:2688
	v_mul_f32_e32 v25, v25, v137
	v_cvt_pk_bf16_f32 v25, v25, v0
	ds_write_b16 v146, v25 offset:2944
	v_mul_f32_e32 v26, v26, v138
	v_cvt_pk_bf16_f32 v26, v26, v0
	ds_write_b16 v146, v26 offset:4224
	v_mul_f32_e32 v27, v27, v139
	v_cvt_pk_bf16_f32 v27, v27, v0
	ds_write_b16 v146, v27 offset:4480
	v_mul_f32_e32 v28, v28, v140
	v_cvt_pk_bf16_f32 v28, v28, v0
	ds_write_b16 v146, v28 offset:4736
	v_mul_f32_e32 v29, v29, v141
	v_cvt_pk_bf16_f32 v29, v29, v0
	ds_write_b16 v146, v29 offset:4992
	v_mul_f32_e32 v30, v30, v142
	v_cvt_pk_bf16_f32 v30, v30, v0
	ds_write_b16 v146, v30 offset:6272
	v_mul_f32_e32 v31, v31, v143
	v_cvt_pk_bf16_f32 v31, v31, v0
	ds_write_b16 v146, v31 offset:6528
	v_mul_f32_e32 v32, v32, v144
	v_cvt_pk_bf16_f32 v32, v32, v0
	ds_write_b16 v146, v32 offset:6784
	v_mul_f32_e32 v33, v33, v145
	v_cvt_pk_bf16_f32 v33, v33, v0
	ds_write_b16 v146, v33 offset:7040
	v_mul_f32_e32 v2, v2, v130
	v_cvt_pk_bf16_f32 v2, v2, v0
	ds_write_b16 v146, v2 offset:192
	v_mul_f32_e32 v3, v3, v131
	v_cvt_pk_bf16_f32 v3, v3, v0
	ds_write_b16 v146, v3 offset:448
	v_mul_f32_e32 v4, v4, v132
	v_cvt_pk_bf16_f32 v4, v4, v0
	ds_write_b16 v146, v4 offset:704
	v_mul_f32_e32 v5, v5, v133
	v_cvt_pk_bf16_f32 v5, v5, v0
	ds_write_b16 v146, v5 offset:960
	v_mul_f32_e32 v6, v6, v134
	v_cvt_pk_bf16_f32 v6, v6, v0
	ds_write_b16 v146, v6 offset:2240
	v_mul_f32_e32 v7, v7, v135
	v_cvt_pk_bf16_f32 v7, v7, v0
	ds_write_b16 v146, v7 offset:2496
	v_mul_f32_e32 v8, v8, v136
	v_cvt_pk_bf16_f32 v8, v8, v0
	ds_write_b16 v146, v8 offset:2752
	v_mul_f32_e32 v9, v9, v137
	v_cvt_pk_bf16_f32 v9, v9, v0
	ds_write_b16 v146, v9 offset:3008
	v_mul_f32_e32 v10, v10, v138
	v_cvt_pk_bf16_f32 v10, v10, v0
	ds_write_b16 v146, v10 offset:4288
	v_mul_f32_e32 v11, v11, v139
	v_cvt_pk_bf16_f32 v11, v11, v0
	ds_write_b16 v146, v11 offset:4544
	v_mul_f32_e32 v12, v12, v140
	v_cvt_pk_bf16_f32 v12, v12, v0
	ds_write_b16 v146, v12 offset:4800
	v_mul_f32_e32 v13, v13, v141
	v_cvt_pk_bf16_f32 v13, v13, v0
	ds_write_b16 v146, v13 offset:5056
	v_mul_f32_e32 v14, v14, v142
	v_cvt_pk_bf16_f32 v14, v14, v0
	ds_write_b16 v146, v14 offset:6336
	v_mul_f32_e32 v15, v15, v143
	v_cvt_pk_bf16_f32 v15, v15, v0
	ds_write_b16 v146, v15 offset:6592
	v_mul_f32_e32 v16, v16, v144
	v_cvt_pk_bf16_f32 v16, v16, v0
	ds_write_b16 v146, v16 offset:6848
	v_mul_f32_e32 v17, v17, v145
	v_cvt_pk_bf16_f32 v17, v17, v0
	ds_write_b16 v146, v17 offset:7104
	s_waitcnt lgkmcnt(0)
	ds_read_b128 v[2:5], v147 offset:0
	ds_read_b128 v[6:9], v147 offset:1024
	ds_read_b128 v[10:13], v147 offset:2048
	ds_read_b128 v[14:17], v147 offset:3072
	ds_read_b128 v[18:21], v147 offset:4096
	ds_read_b128 v[22:25], v147 offset:5120
	ds_read_b128 v[26:29], v147 offset:6144
	ds_read_b128 v[30:33], v147 offset:7168
	s_waitcnt lgkmcnt(7)
	global_store_dwordx4 v[150:151], v[2:5], off offset:256
	s_waitcnt lgkmcnt(6)
	global_store_dwordx4 v[98:99], v[6:9], off offset:256
	s_waitcnt lgkmcnt(5)
	global_store_dwordx4 v[100:101], v[10:13], off offset:256
	s_waitcnt lgkmcnt(4)
	global_store_dwordx4 v[102:103], v[14:17], off offset:256
	s_waitcnt lgkmcnt(3)
	global_store_dwordx4 v[104:105], v[18:21], off offset:256
	s_waitcnt lgkmcnt(2)
	global_store_dwordx4 v[106:107], v[22:25], off offset:256
	s_waitcnt lgkmcnt(1)
	global_store_dwordx4 v[108:109], v[26:29], off offset:256
	s_waitcnt lgkmcnt(0)
	global_store_dwordx4 v[110:111], v[30:33], off offset:256
	s_add_i32 s0, s0, s26
	v_readlane_b32 s28, v250, 11
	v_readlane_b32 s29, v250, 12
	s_movk_i32 s27, 0xff
	s_waitcnt vmcnt(0) lgkmcnt(0)
	s_cmp_lt_i32 s0, s1
	s_barrier
	s_cbranch_scc0 .LBB0_628
